# attention: heavy latent-diff blocks skip SWA; other blocks take latent-SWA + ctx-SWA item
# baseline (speedup 1.0000x reference)
.LBB0_1716:
	s_not_b32 s0, s97
	s_add_i32 s33, s92, s0
	s_mov_b32 s98, s92
	s_cmp_lg_u32 s92, 0x200
	s_cbranch_scc1 .Lswa_gen
	s_movk_i32 s98, 0x100
	s_cmpk_lt_i32 s97, 0x100
	s_cselect_b32 s33, 0x200, s33
.Lswa_gen:
	s_cmpk_gt_i32 s33, 0x1ff
	s_cbranch_scc1 .LBB0_1750
	v_readlane_b32 s0, v253, 6
	v_readlane_b32 s12, v253, 18
	v_readlane_b32 s13, v253, 19
	s_add_u32 s38, s12, 0x80
	v_readlane_b32 s10, v253, 16
	s_addc_u32 s39, s13, 0
	s_lshl_b32 s58, s33, 4
	s_lshl_b32 s59, s98, 4
	v_readlane_b32 s11, v253, 17
	s_add_u32 s34, s10, 0xfff82000
	s_mov_b64 s[30:31], 0x80
	s_addc_u32 s35, s11, -1
	s_lshl_b32 s60, s33, 5
	s_lshl_b32 s61, s98, 5
	s_mov_b32 s37, 0
	s_waitcnt vmcnt(1)
	v_mov_b32_e32 v97, 0
	s_movk_i32 s62, 0x90
	s_mov_b32 s63, 0xf149f2ca
	s_mov_b64 s[40:41], 0x2000
	s_movk_i32 s64, 0xfeff
	s_movk_i32 s65, 0x101
	s_movk_i32 s66, 0xfefe
	v_mov_b32_e32 v115, 0x80
	v_mov_b32_e32 v117, 0xf149f2ca
	v_readlane_b32 s1, v253, 7
	v_readlane_b32 s2, v253, 8
	v_readlane_b32 s3, v253, 9
	v_readlane_b32 s4, v253, 10
	v_readlane_b32 s5, v253, 11
	v_readlane_b32 s6, v253, 12
	v_readlane_b32 s7, v253, 13
	v_readlane_b32 s8, v253, 14
	v_readlane_b32 s9, v253, 15
	v_readlane_b32 s14, v253, 20
	v_readlane_b32 s15, v253, 21
	s_branch .LBB0_1721

.LBB0_1720:
	s_waitcnt vmcnt(0)
	v_div_scale_f32 v35, s[0:1], v32, v32, 1.0
	v_rcp_f32_e32 v36, v35
	v_div_scale_f32 v37, vcc, 1.0, v32, 1.0
	v_add_f32_e32 v33, v33, v34
	v_fma_f32 v38, -v35, v36, 1.0
	v_fmac_f32_e32 v36, v38, v36
	v_mul_f32_e32 v38, v37, v36
	v_fma_f32 v39, -v35, v38, v37
	v_fmac_f32_e32 v38, v39, v36
	v_div_scale_f32 v34, s[0:1], v33, v33, 1.0
	v_fma_f32 v35, -v35, v38, v37
	v_rcp_f32_e32 v37, v34
	v_div_fmas_f32 v35, v35, v36, v38
	v_div_fixup_f32 v32, v35, v32, 1.0
	v_readlane_b32 s0, v253, 50
	v_fma_f32 v35, -v34, v37, 1.0
	v_fmac_f32_e32 v37, v35, v37
	v_div_scale_f32 v35, vcc, 1.0, v33, 1.0
	v_mul_f32_e32 v36, v35, v37
	v_fma_f32 v38, -v34, v36, v35
	v_fmac_f32_e32 v36, v38, v37
	v_fma_f32 v34, -v34, v36, v35
	v_div_fmas_f32 v34, v34, v37, v36
	v_lshlrev_b64 v[36:37], 11, v[102:103]
	v_pk_mul_f32 v[24:25], v[24:25], v[32:33] op_sel_hi:[1,0]
	v_pk_mul_f32 v[26:27], v[26:27], v[32:33] op_sel_hi:[1,0]
	v_readlane_b32 s12, v253, 62
	v_readlane_b32 s13, v253, 63
	v_cvt_pk_bf16_f32 v24, v24, v25
	v_cvt_pk_bf16_f32 v25, v26, v27
	v_lshl_add_u64 v[26:27], s[12:13], 0, v[36:37]
	v_lshlrev_b64 v[36:37], 1, v[98:99]
	v_lshl_add_u64 v[26:27], v[26:27], 0, v[36:37]
	v_lshlrev_b64 v[38:39], 1, v[96:97]
	v_pk_mul_f32 v[16:17], v[32:33], v[16:17] op_sel_hi:[0,1]
	v_pk_mul_f32 v[18:19], v[32:33], v[18:19] op_sel_hi:[0,1]
	v_lshl_add_u64 v[26:27], v[26:27], 0, v[38:39]
	v_cvt_pk_bf16_f32 v16, v16, v17
	v_cvt_pk_bf16_f32 v17, v18, v19
	global_store_dwordx2 v[26:27], v[16:17], off offset:32
	v_pk_mul_f32 v[16:17], v[32:33], v[20:21] op_sel_hi:[0,1]
	v_pk_mul_f32 v[18:19], v[32:33], v[22:23] op_sel_hi:[0,1]
	v_cvt_pk_bf16_f32 v16, v16, v17
	v_cvt_pk_bf16_f32 v17, v18, v19
	global_store_dwordx2 v[26:27], v[16:17], off offset:64
	v_pk_mul_f32 v[16:17], v[32:33], v[28:29] op_sel_hi:[0,1]
	v_pk_mul_f32 v[18:19], v[32:33], v[30:31] op_sel_hi:[0,1]
	v_div_fixup_f32 v34, v34, v33, 1.0
	v_cvt_pk_bf16_f32 v16, v16, v17
	v_cvt_pk_bf16_f32 v17, v18, v19
	global_store_dwordx2 v[26:27], v[16:17], off offset:96
	v_lshlrev_b64 v[16:17], 11, v[100:101]
	v_pk_mul_f32 v[4:5], v[34:35], v[4:5] op_sel_hi:[0,1]
	v_pk_mul_f32 v[6:7], v[34:35], v[6:7] op_sel_hi:[0,1]
	v_cvt_pk_bf16_f32 v4, v4, v5
	v_cvt_pk_bf16_f32 v5, v6, v7
	v_lshl_add_u64 v[6:7], s[12:13], 0, v[16:17]
	v_lshl_add_u64 v[6:7], v[6:7], 0, v[36:37]
	v_pk_mul_f32 v[0:1], v[34:35], v[0:1] op_sel_hi:[0,1]
	v_pk_mul_f32 v[2:3], v[34:35], v[2:3] op_sel_hi:[0,1]
	v_lshl_add_u64 v[6:7], v[6:7], 0, v[38:39]
	v_cvt_pk_bf16_f32 v0, v0, v1
	v_cvt_pk_bf16_f32 v1, v2, v3
	global_store_dwordx2 v[6:7], v[0:1], off offset:32
	v_pk_mul_f32 v[0:1], v[34:35], v[8:9] op_sel_hi:[0,1]
	v_pk_mul_f32 v[2:3], v[34:35], v[10:11] op_sel_hi:[0,1]
	v_cvt_pk_bf16_f32 v0, v0, v1
	v_cvt_pk_bf16_f32 v1, v2, v3
	global_store_dwordx2 v[6:7], v[0:1], off offset:64
	v_pk_mul_f32 v[0:1], v[34:35], v[12:13] op_sel_hi:[0,1]
	v_pk_mul_f32 v[2:3], v[34:35], v[14:15] op_sel_hi:[0,1]
	s_add_i32 s33, s33, s98
	s_add_i32 s58, s58, s59
	s_add_i32 s60, s60, s61
	v_cvt_pk_bf16_f32 v0, v0, v1
	v_cvt_pk_bf16_f32 v1, v2, v3
	s_cmpk_lt_i32 s33, 0x200
	v_readlane_b32 s1, v253, 51
	v_readlane_b32 s2, v253, 52
	v_readlane_b32 s3, v253, 53
	v_readlane_b32 s4, v253, 54
	v_readlane_b32 s5, v253, 55
	v_readlane_b32 s6, v253, 56
	v_readlane_b32 s7, v253, 57
	v_readlane_b32 s8, v253, 58
	v_readlane_b32 s9, v253, 59
	v_readlane_b32 s10, v253, 60
	v_readlane_b32 s11, v253, 61
	v_readlane_b32 s14, v255, 0
	v_readlane_b32 s15, v255, 1
	global_store_dwordx2 v[26:27], v[24:25], off
	global_store_dwordx2 v[6:7], v[4:5], off
	global_store_dwordx2 v[6:7], v[0:1], off offset:96
	s_cbranch_scc0 .LBB0_1749
